# scans: one static s_setprio 1 for waves 0-3 (forward direction) before the scan loop, s_setprio 0 after it
# speedup vs baseline: 1.0063x; 1.0063x over previous
; __device__ __forceinline__ int fresh_lane() { int t; asm volatile("v_mbcnt_lo_u32_b32 %0, -1, 0\n\tv_mbcnt_hi_u32_b32 %0, -1, %0" : "=v"(t)); return t; }
;     ...
;     const int b = bh >> 2, h = bh & 3;
;     const int lane = fresh_lane(), dir = F.wave >> 2, wq = F.wave & 3, lr = lane & 15, lq = lane >> 4;
.LBB0_345:
	s_or_b64 exec, exec, s[10:11]
	s_cmp_ge_u32 s64, 0x100
	s_cbranch_scc1 .Lprio_m
	s_setprio 1
